# MLA unit epilogue: the 4 gate-row loads issued together (were serial load/vmcnt(0)/use/store groups), with store-data WAR and permlane wait states
# speedup vs baseline: 1.0103x; 1.0042x over previous
.LBB0_974:
	s_or_b64 exec, exec, s[42:43]
	v_mov_b64_e32 v[12:13], s[72:73]
	v_mad_u64_u32 v[12:13], s[24:25], v2, s52, v[12:13]
	s_lshl_b32 s6, s33, 7
	v_mad_i32_i24 v13, v3, s52, v13
	v_lshl_add_u64 v[48:49], v[12:13], 0, s[6:7]
	v_lshlrev_b32_e32 v0, 1, v207
	v_lshl_add_u64 v[56:57], v[48:49], 0, v[0:1]
	global_load_dwordx4 v[58:61], v[56:57], off offset:3072
	global_load_dwordx4 v[152:155], v[56:57], off offset:3104
	global_load_dwordx4 v[156:159], v[56:57], off offset:3136
	global_load_dwordx4 v[160:163], v[56:57], off offset:3168
	s_add_u32 s42, s86, s6
	v_lshlrev_b64 v[48:49], 11, v[2:3]
	s_addc_u32 s43, s87, 0
	v_lshl_add_u64 v[48:49], s[42:43], 0, v[48:49]
	v_lshl_add_u64 v[48:49], v[48:49], 0, v[0:1]
	v_or_b32_e32 v2, 32, v2
	s_waitcnt vmcnt(0)
	v_permlane32_swap_b32_e32 v58, v60
	v_permlane32_swap_b32_e32 v59, v61
	v_lshlrev_b32_e32 v62, 16, v58
	v_and_b32_e32 v58, 0xffff0000, v58
	v_lshlrev_b32_e32 v63, 16, v59
	v_and_b32_e32 v59, 0xffff0000, v59
	v_lshlrev_b32_e32 v94, 16, v60
	v_and_b32_e32 v60, 0xffff0000, v60
	v_lshlrev_b32_e32 v95, 16, v61
	v_and_b32_e32 v61, 0xffff0000, v61
	v_mul_f32_e32 v111, 0xbfb8aa3b, v58
	v_mul_f32_e32 v117, 0xbfb8aa3b, v59
	v_mul_f32_e32 v119, 0xbfb8aa3b, v60
	v_mul_f32_e32 v121, 0xbfb8aa3b, v61
	v_mul_f32_e32 v110, 0xbfb8aa3b, v62
	v_mul_f32_e32 v116, 0xbfb8aa3b, v63
	v_mul_f32_e32 v118, 0xbfb8aa3b, v94
	v_mul_f32_e32 v120, 0xbfb8aa3b, v95
	v_exp_f32_e32 v111, v111
	v_exp_f32_e32 v117, v117
	v_exp_f32_e32 v119, v119
	v_exp_f32_e32 v121, v121
	v_exp_f32_e32 v110, v110
	v_exp_f32_e32 v116, v116
	v_exp_f32_e32 v118, v118
	v_exp_f32_e32 v120, v120
	v_add_f32_e32 v111, 1.0, v111
	v_add_f32_e32 v117, 1.0, v117
	v_add_f32_e32 v119, 1.0, v119
	v_add_f32_e32 v121, 1.0, v121
	v_add_f32_e32 v110, 1.0, v110
	v_add_f32_e32 v116, 1.0, v116
	v_add_f32_e32 v118, 1.0, v118
	v_add_f32_e32 v120, 1.0, v120
	v_rcp_f32_e32 v111, v111
	v_rcp_f32_e32 v117, v117
	v_rcp_f32_e32 v119, v119
	v_rcp_f32_e32 v121, v121
	v_rcp_f32_e32 v110, v110
	v_rcp_f32_e32 v116, v116
	v_rcp_f32_e32 v118, v118
	v_rcp_f32_e32 v120, v120
	v_mul_f32_e32 v58, v111, v58
	v_mul_f32_e32 v59, v117, v59
	v_mul_f32_e32 v60, v119, v60
	v_mul_f32_e32 v61, v121, v61
	v_mul_f32_e32 v62, v110, v62
	v_mul_f32_e32 v63, v116, v63
	v_mul_f32_e32 v94, v118, v94
	v_mul_f32_e32 v95, v120, v95
	v_mul_f32_e32 v58, v65, v58
	v_mul_f32_e32 v59, v67, v59
	v_mul_f32_e32 v60, v69, v60
	v_mul_f32_e32 v61, v71, v61
	v_mul_f32_e32 v62, v64, v62
	v_mul_f32_e32 v63, v66, v63
	v_mul_f32_e32 v64, v68, v94
	v_mul_f32_e32 v65, v70, v95
	v_cvt_pk_bf16_f32 v58, v62, v58
	v_cvt_pk_bf16_f32 v59, v63, v59
	v_cvt_pk_bf16_f32 v60, v64, v60
	v_cvt_pk_bf16_f32 v61, v65, v61
	s_nop 0
	v_permlane32_swap_b32_e32 v58, v60
	v_permlane32_swap_b32_e32 v59, v61
	global_store_dwordx4 v[48:49], v[58:61], off
	s_nop 1
	v_mov_b64_e32 v[58:59], v[152:153]
	v_mov_b64_e32 v[60:61], v[154:155]
	s_nop 1
	v_permlane32_swap_b32_e32 v58, v60
	v_permlane32_swap_b32_e32 v59, v61
	v_lshlrev_b32_e32 v62, 16, v58
	v_and_b32_e32 v58, 0xffff0000, v58
	v_lshlrev_b32_e32 v63, 16, v59
	v_and_b32_e32 v59, 0xffff0000, v59
	v_lshlrev_b32_e32 v64, 16, v60
	v_and_b32_e32 v60, 0xffff0000, v60
	v_lshlrev_b32_e32 v65, 16, v61
	v_and_b32_e32 v61, 0xffff0000, v61
	v_mul_f32_e32 v67, 0xbfb8aa3b, v58
	v_mul_f32_e32 v69, 0xbfb8aa3b, v59
	v_mul_f32_e32 v71, 0xbfb8aa3b, v60
	v_mul_f32_e32 v95, 0xbfb8aa3b, v61
	v_mul_f32_e32 v66, 0xbfb8aa3b, v62
	v_mul_f32_e32 v68, 0xbfb8aa3b, v63
	v_mul_f32_e32 v70, 0xbfb8aa3b, v64
	v_mul_f32_e32 v94, 0xbfb8aa3b, v65
	v_exp_f32_e32 v67, v67
	v_exp_f32_e32 v69, v69
	v_exp_f32_e32 v71, v71
	v_exp_f32_e32 v95, v95
	v_exp_f32_e32 v66, v66
	v_exp_f32_e32 v68, v68
	v_exp_f32_e32 v70, v70
	v_exp_f32_e32 v94, v94
	v_add_f32_e32 v67, 1.0, v67
	v_add_f32_e32 v69, 1.0, v69
	v_add_f32_e32 v71, 1.0, v71
	v_add_f32_e32 v95, 1.0, v95
	v_add_f32_e32 v66, 1.0, v66
	v_add_f32_e32 v68, 1.0, v68
	v_add_f32_e32 v70, 1.0, v70
	v_add_f32_e32 v94, 1.0, v94
	v_rcp_f32_e32 v67, v67
	v_rcp_f32_e32 v69, v69
	v_rcp_f32_e32 v71, v71
	v_rcp_f32_e32 v95, v95
	v_rcp_f32_e32 v66, v66
	v_rcp_f32_e32 v68, v68
	v_rcp_f32_e32 v70, v70
	v_rcp_f32_e32 v94, v94
	v_mul_f32_e32 v58, v67, v58
	v_mul_f32_e32 v59, v69, v59
	v_mul_f32_e32 v60, v71, v60
	v_mul_f32_e32 v61, v95, v61
	v_mul_f32_e32 v62, v66, v62
	v_mul_f32_e32 v63, v68, v63
	v_mul_f32_e32 v64, v70, v64
	v_mul_f32_e32 v65, v94, v65
	v_mul_f32_e32 v58, v73, v58
	v_mul_f32_e32 v59, v75, v59
	v_mul_f32_e32 v60, v77, v60
	v_mul_f32_e32 v61, v79, v61
	v_mul_f32_e32 v62, v72, v62
	v_mul_f32_e32 v63, v74, v63
	v_mul_f32_e32 v64, v76, v64
	v_mul_f32_e32 v65, v78, v65
	v_cvt_pk_bf16_f32 v58, v62, v58
	v_cvt_pk_bf16_f32 v59, v63, v59
	v_cvt_pk_bf16_f32 v60, v64, v60
	v_cvt_pk_bf16_f32 v61, v65, v61
	v_add_f32_e32 v62, 0, v96
	v_permlane32_swap_b32_e32 v58, v60
	v_permlane32_swap_b32_e32 v59, v61
	global_store_dwordx4 v[48:49], v[58:61], off offset:32
	s_nop 1
	v_mov_b64_e32 v[58:59], v[156:157]
	v_mov_b64_e32 v[60:61], v[158:159]
	s_nop 1
	v_add_f32_e32 v62, v97, v62
	v_add_f32_e32 v62, v98, v62
	v_add_f32_e32 v62, v99, v62
	v_add_f32_e32 v62, v100, v62
	v_add_f32_e32 v62, v101, v62
	v_add_f32_e32 v62, v102, v62
	v_add_f32_e32 v62, v103, v62
	v_add_f32_e32 v62, v104, v62
	v_add_f32_e32 v62, v105, v62
	v_add_f32_e32 v62, v106, v62
	v_add_f32_e32 v62, v107, v62
	v_add_f32_e32 v62, v112, v62
	v_add_f32_e32 v62, v113, v62
	v_add_f32_e32 v62, v114, v62
	v_add_f32_e32 v62, v115, v62
	v_add_f32_e32 v62, v108, v62
	v_add_f32_e32 v62, v109, v62
	v_permlane32_swap_b32_e32 v58, v60
	v_permlane32_swap_b32_e32 v59, v61
	v_lshlrev_b32_e32 v64, 16, v59
	v_and_b32_e32 v59, 0xffff0000, v59
	v_lshlrev_b32_e32 v65, 16, v60
	v_and_b32_e32 v60, 0xffff0000, v60
	v_lshlrev_b32_e32 v63, 16, v58
	v_and_b32_e32 v58, 0xffff0000, v58
	v_lshlrev_b32_e32 v66, 16, v61
	v_and_b32_e32 v61, 0xffff0000, v61
	v_mul_f32_e32 v70, 0xbfb8aa3b, v59
	v_mul_f32_e32 v71, 0xbfb8aa3b, v65
	v_mul_f32_e32 v72, 0xbfb8aa3b, v60
	v_mul_f32_e32 v67, 0xbfb8aa3b, v63
	v_mul_f32_e32 v68, 0xbfb8aa3b, v58
	v_mul_f32_e32 v69, 0xbfb8aa3b, v64
	v_mul_f32_e32 v73, 0xbfb8aa3b, v66
	v_mul_f32_e32 v74, 0xbfb8aa3b, v61
	v_exp_f32_e32 v70, v70
	v_exp_f32_e32 v71, v71
	v_exp_f32_e32 v72, v72
	v_exp_f32_e32 v67, v67
	v_exp_f32_e32 v68, v68
	v_exp_f32_e32 v69, v69
	v_exp_f32_e32 v73, v73
	v_exp_f32_e32 v74, v74
	v_add_f32_e32 v70, 1.0, v70
	v_add_f32_e32 v71, 1.0, v71
	v_add_f32_e32 v72, 1.0, v72
	v_add_f32_e32 v67, 1.0, v67
	v_add_f32_e32 v68, 1.0, v68
	v_add_f32_e32 v69, 1.0, v69
	v_add_f32_e32 v73, 1.0, v73
	v_add_f32_e32 v74, 1.0, v74
	v_rcp_f32_e32 v70, v70
	v_rcp_f32_e32 v71, v71
	v_rcp_f32_e32 v72, v72
	v_rcp_f32_e32 v67, v67
	v_rcp_f32_e32 v68, v68
	v_rcp_f32_e32 v69, v69
	v_rcp_f32_e32 v73, v73
	v_rcp_f32_e32 v74, v74
	v_mul_f32_e32 v59, v70, v59
	v_mul_f32_e32 v65, v71, v65
	v_mul_f32_e32 v60, v72, v60
	v_mul_f32_e32 v63, v67, v63
	v_mul_f32_e32 v58, v68, v58
	v_mul_f32_e32 v64, v69, v64
	v_mul_f32_e32 v66, v73, v66
	v_mul_f32_e32 v61, v74, v61
	v_mul_f32_e32 v51, v51, v59
	v_mul_f32_e32 v52, v52, v65
	v_mul_f32_e32 v53, v53, v60
	v_mul_f32_e32 v54, v54, v63
	v_mul_f32_e32 v55, v55, v58
	v_mul_f32_e32 v58, v50, v64
	v_mul_f32_e32 v14, v14, v66
	v_mul_f32_e32 v15, v15, v61
	v_cvt_pk_bf16_f32 v50, v54, v55
	v_cvt_pk_bf16_f32 v51, v58, v51
	v_cvt_pk_bf16_f32 v52, v52, v53
	v_cvt_pk_bf16_f32 v53, v14, v15
	v_add_f32_e32 v14, v80, v62
	v_permlane32_swap_b32_e32 v50, v52
	v_permlane32_swap_b32_e32 v51, v53
	global_store_dwordx4 v[48:49], v[50:53], off offset:64
	s_nop 1
	v_mov_b64_e32 v[50:51], v[160:161]
	v_mov_b64_e32 v[52:53], v[162:163]
	s_nop 1
	v_add_f32_e32 v14, v81, v14
	v_add_f32_e32 v14, v82, v14
	v_add_f32_e32 v14, v83, v14
	v_add_f32_e32 v14, v84, v14
	v_add_f32_e32 v14, v85, v14
	v_add_f32_e32 v14, v86, v14
	v_add_f32_e32 v14, v87, v14
	v_add_f32_e32 v14, v88, v14
	v_add_f32_e32 v14, v89, v14
	v_add_f32_e32 v14, v90, v14
	v_add_f32_e32 v14, v91, v14
	v_add_f32_e32 v14, v92, v14
	v_add_f32_e32 v14, v93, v14
	v_add_f32_e32 v14, v206, v14
	v_mov_b32_e32 v15, v14
	s_nop 1
	v_permlane32_swap_b32_e32 v14, v15
	v_add_f32_e32 v14, v14, v15
	v_min_u32_e32 v242, v242, v14
	v_max_u32_e32 v243, v243, v14
	v_div_scale_f32 v15, s[24:25], v14, v14, 1.0
	v_rcp_f32_e32 v54, v15
	v_div_scale_f32 v55, vcc, 1.0, v14, 1.0
	v_fma_f32 v56, -v15, v54, 1.0
	v_fmac_f32_e32 v54, v56, v54
	v_mul_f32_e32 v56, v55, v54
	v_fma_f32 v57, -v15, v56, v55
	v_fmac_f32_e32 v56, v57, v54
	v_fma_f32 v15, -v15, v56, v55
	v_div_fmas_f32 v15, v15, v54, v56
	v_div_fixup_f32 v54, v15, v14, 1.0
	v_pk_mul_f32 v[32:33], v[32:33], v[54:55] op_sel_hi:[1,0]
	v_pk_mul_f32 v[14:15], v[30:31], v[54:55] op_sel_hi:[1,0]
	v_mul_f32_e32 v30, v33, v33
	v_pk_mul_f32 v[34:35], v[34:35], v[54:55] op_sel_hi:[1,0]
	v_fmac_f32_e32 v30, v32, v32
	v_fmac_f32_e32 v30, v34, v34
	v_pk_mul_f32 v[36:37], v[36:37], v[54:55] op_sel_hi:[1,0]
	v_fmac_f32_e32 v30, v35, v35
	v_fmac_f32_e32 v30, v36, v36
	v_pk_mul_f32 v[38:39], v[38:39], v[54:55] op_sel_hi:[1,0]
	v_fmac_f32_e32 v30, v37, v37
	v_fmac_f32_e32 v30, v38, v38
	v_pk_mul_f32 v[40:41], v[40:41], v[54:55] op_sel_hi:[1,0]
	v_fmac_f32_e32 v30, v39, v39
	v_fmac_f32_e32 v30, v40, v40
	v_pk_mul_f32 v[42:43], v[42:43], v[54:55] op_sel_hi:[1,0]
	v_fmac_f32_e32 v30, v41, v41
	v_fmac_f32_e32 v30, v42, v42
	v_pk_mul_f32 v[44:45], v[44:45], v[54:55] op_sel_hi:[1,0]
	v_fmac_f32_e32 v30, v43, v43
	v_fmac_f32_e32 v30, v44, v44
	v_pk_mul_f32 v[46:47], v[46:47], v[54:55] op_sel_hi:[1,0]
	v_fmac_f32_e32 v30, v45, v45
	v_fmac_f32_e32 v30, v46, v46
	v_pk_mul_f32 v[16:17], v[16:17], v[54:55] op_sel_hi:[1,0]
	v_fmac_f32_e32 v30, v47, v47
	v_fmac_f32_e32 v30, v16, v16
	v_pk_mul_f32 v[28:29], v[28:29], v[54:55] op_sel_hi:[1,0]
	v_pk_mul_f32 v[26:27], v[26:27], v[54:55] op_sel_hi:[1,0]
	v_pk_mul_f32 v[24:25], v[24:25], v[54:55] op_sel_hi:[1,0]
	v_pk_mul_f32 v[22:23], v[22:23], v[54:55] op_sel_hi:[1,0]
	v_pk_mul_f32 v[20:21], v[20:21], v[54:55] op_sel_hi:[1,0]
	v_pk_mul_f32 v[18:19], v[18:19], v[54:55] op_sel_hi:[1,0]
	v_fmac_f32_e32 v30, v17, v17
	v_fmac_f32_e32 v30, v18, v18
	v_fmac_f32_e32 v30, v19, v19
	v_fmac_f32_e32 v30, v20, v20
	v_fmac_f32_e32 v30, v21, v21
	v_fmac_f32_e32 v30, v22, v22
	v_fmac_f32_e32 v30, v23, v23
	v_fmac_f32_e32 v30, v24, v24
	v_fmac_f32_e32 v30, v25, v25
	v_fmac_f32_e32 v30, v26, v26
	v_fmac_f32_e32 v30, v27, v27
	v_fmac_f32_e32 v30, v28, v28
	v_fmac_f32_e32 v30, v29, v29
	v_fmac_f32_e32 v30, v14, v14
	v_mov_b32_e32 v31, v52
	v_mov_b32_e32 v52, v53
	s_nop 0
	v_permlane32_swap_b32_e32 v50, v31
	v_permlane32_swap_b32_e32 v51, v52
	v_lshlrev_b32_e32 v55, 16, v31
	v_and_b32_e32 v31, 0xffff0000, v31
	v_lshlrev_b32_e32 v53, 16, v50
	v_and_b32_e32 v50, 0xffff0000, v50
	v_lshlrev_b32_e32 v54, 16, v51
	v_and_b32_e32 v51, 0xffff0000, v51
	v_lshlrev_b32_e32 v56, 16, v52
	v_and_b32_e32 v52, 0xffff0000, v52
	v_mul_f32_e32 v61, 0xbfb8aa3b, v55
	v_mul_f32_e32 v62, 0xbfb8aa3b, v31
	v_mul_f32_e32 v57, 0xbfb8aa3b, v53
	v_mul_f32_e32 v58, 0xbfb8aa3b, v50
	v_mul_f32_e32 v59, 0xbfb8aa3b, v54
	v_mul_f32_e32 v60, 0xbfb8aa3b, v51
	v_mul_f32_e32 v63, 0xbfb8aa3b, v56
	v_mul_f32_e32 v64, 0xbfb8aa3b, v52
	v_exp_f32_e32 v61, v61
	v_exp_f32_e32 v62, v62
	v_exp_f32_e32 v57, v57
	v_exp_f32_e32 v58, v58
	v_exp_f32_e32 v59, v59
	v_exp_f32_e32 v60, v60
	v_exp_f32_e32 v63, v63
	v_exp_f32_e32 v64, v64
	v_add_f32_e32 v61, 1.0, v61
	v_add_f32_e32 v62, 1.0, v62
	v_add_f32_e32 v57, 1.0, v57
	v_add_f32_e32 v58, 1.0, v58
	v_add_f32_e32 v59, 1.0, v59
	v_add_f32_e32 v60, 1.0, v60
	v_add_f32_e32 v63, 1.0, v63
	v_add_f32_e32 v64, 1.0, v64
	v_rcp_f32_e32 v61, v61
	v_rcp_f32_e32 v62, v62
	v_rcp_f32_e32 v57, v57
	v_rcp_f32_e32 v58, v58
	v_rcp_f32_e32 v59, v59
	v_rcp_f32_e32 v60, v60
	v_rcp_f32_e32 v63, v63
	v_rcp_f32_e32 v64, v64
	v_mul_f32_e32 v55, v61, v55
	v_mul_f32_e32 v31, v62, v31
	v_mul_f32_e32 v53, v57, v53
	v_mul_f32_e32 v50, v58, v50
	v_mul_f32_e32 v54, v59, v54
	v_mul_f32_e32 v51, v60, v51
	v_mul_f32_e32 v56, v63, v56
	v_mul_f32_e32 v52, v64, v52
	v_mul_f32_e32 v6, v6, v55
	v_mul_f32_e32 v7, v7, v31
	v_mul_f32_e32 v10, v10, v53
	v_mul_f32_e32 v11, v11, v50
	v_mul_f32_e32 v8, v8, v54
	v_mul_f32_e32 v9, v9, v51
	v_mul_f32_e32 v31, v4, v56
	v_mul_f32_e32 v50, v5, v52
	v_cvt_pk_bf16_f32 v4, v10, v11
	v_cvt_pk_bf16_f32 v5, v8, v9
	v_cvt_pk_bf16_f32 v6, v6, v7
	v_cvt_pk_bf16_f32 v7, v31, v50
	v_fmac_f32_e32 v30, v15, v15
	v_permlane32_swap_b32_e32 v4, v6
	v_permlane32_swap_b32_e32 v5, v7
	global_store_dwordx4 v[48:49], v[4:7], off offset:96
	s_nop 1
	v_mov_b32_e32 v4, v30
	s_nop 1
	v_permlane32_swap_b32_e32 v30, v4
	s_and_saveexec_b64 s[44:45], s[0:1]
	s_cbranch_execz .LBB0_954
	v_add_f32_e32 v6, v30, v4
	v_lshlrev_b64 v[4:5], 5, v[2:3]
	v_lshl_add_u64 v[4:5], s[40:41], 0, v[4:5]
	global_store_dword v[4:5], v6, off
	s_branch .LBB0_954
